# gla_s1 and gla_s3 state-update sections: k~T fragment LDS reads kept four deep ahead of their MFMAs, decay reads double-buffered (MFMA/LDS interleave lever)
# speedup vs baseline: 1.0081x; 1.0059x over previous
.LBB0_618:
	v_cndmask_b32_e64 v129, 1.0, v129, s[0:1]
	s_add_i32 s26, s26, s15
	v_mul_f32_e32 v125, v125, v129
	v_add_u32_e32 v129, s26, v113
	ds_read_b128 v[154:157], v129
	ds_read_b128 v[170:173], v129 offset:32
	ds_read_b128 v[174:177], v129 offset:64
	ds_read_b128 v[178:181], v129 offset:96
	s_add_i32 s9, s16, s25
	s_waitcnt lgkmcnt(0)
	v_pk_mul_f32 v[48:49], v[48:49], v[154:155]
	v_pk_mul_f32 v[52:53], v[52:53], v[170:171]
	v_pk_mul_f32 v[56:57], v[56:57], v[174:175]
	v_pk_mul_f32 v[60:61], v[60:61], v[178:179]
	v_pk_mul_f32 v[62:63], v[62:63], v[180:181]
	v_pk_mul_f32 v[58:59], v[58:59], v[176:177]
	v_pk_mul_f32 v[54:55], v[54:55], v[172:173]
	v_pk_mul_f32 v[50:51], v[50:51], v[156:157]
	ds_read_b128 v[154:157], v129 offset:128
	ds_read_b128 v[170:173], v129 offset:160
	ds_read_b128 v[174:177], v129 offset:192
	ds_read_b128 v[178:181], v129 offset:224
	s_add_i32 s24, s24, 1
	s_waitcnt lgkmcnt(0)
	v_pk_mul_f32 v[32:33], v[32:33], v[154:155]
	v_pk_mul_f32 v[36:37], v[36:37], v[170:171]
	v_pk_mul_f32 v[40:41], v[40:41], v[174:175]
	v_pk_mul_f32 v[44:45], v[44:45], v[178:179]
	v_pk_mul_f32 v[46:47], v[46:47], v[180:181]
	v_pk_mul_f32 v[42:43], v[42:43], v[176:177]
	v_pk_mul_f32 v[38:39], v[38:39], v[172:173]
	v_pk_mul_f32 v[34:35], v[34:35], v[156:157]
	ds_read_b128 v[154:157], v129 offset:256
	ds_read_b128 v[170:173], v129 offset:288
	ds_read_b128 v[174:177], v129 offset:320
	ds_read_b128 v[178:181], v129 offset:352
	s_add_i32 s8, s8, 4
	s_waitcnt lgkmcnt(0)
	v_pk_mul_f32 v[16:17], v[16:17], v[154:155]
	v_pk_mul_f32 v[20:21], v[20:21], v[170:171]
	v_pk_mul_f32 v[24:25], v[24:25], v[174:175]
	v_pk_mul_f32 v[28:29], v[28:29], v[178:179]
	v_pk_mul_f32 v[30:31], v[30:31], v[180:181]
	v_pk_mul_f32 v[26:27], v[26:27], v[176:177]
	v_pk_mul_f32 v[22:23], v[22:23], v[172:173]
	v_pk_mul_f32 v[18:19], v[18:19], v[156:157]
	ds_read_b128 v[154:157], v129 offset:384
	ds_read_b128 v[170:173], v129 offset:416
	ds_read_b128 v[174:177], v129 offset:448
	ds_read_b128 v[178:181], v129 offset:480
	v_add_u32_e32 v129, s9, v119
	s_waitcnt lgkmcnt(0)
	v_pk_mul_f32 v[0:1], v[0:1], v[154:155]
	v_pk_mul_f32 v[2:3], v[2:3], v[156:157]
	v_pk_mul_f32 v[4:5], v[4:5], v[170:171]
	v_pk_mul_f32 v[6:7], v[6:7], v[172:173]
	v_pk_mul_f32 v[8:9], v[8:9], v[174:175]
	v_pk_mul_f32 v[10:11], v[10:11], v[176:177]
	v_pk_mul_f32 v[12:13], v[12:13], v[178:179]
	v_pk_mul_f32 v[14:15], v[14:15], v[180:181]
	ds_read_b128 v[154:157], v129
	ds_read_b128 v[170:173], v129 offset:4096
	ds_read_b128 v[174:177], v129 offset:8192
	ds_read_b128 v[178:181], v129 offset:12288
	s_waitcnt lgkmcnt(3)
	v_mfma_f32_32x32x16_bf16 v[48:63], v[154:157], v[108:111], v[48:63]
	ds_read_b128 v[154:157], v129 offset:1024
	s_waitcnt lgkmcnt(3)
	v_mfma_f32_32x32x16_bf16 v[32:47], v[170:173], v[108:111], v[32:47]
	ds_read_b128 v[170:173], v129 offset:5120
	s_waitcnt lgkmcnt(3)
	v_mfma_f32_32x32x16_bf16 v[16:31], v[174:177], v[108:111], v[16:31]
	ds_read_b128 v[174:177], v129 offset:9216
	s_waitcnt lgkmcnt(3)
	v_mfma_f32_32x32x16_bf16 v[0:15], v[178:181], v[108:111], v[0:15]
	ds_read_b128 v[178:181], v129 offset:13312
	s_waitcnt lgkmcnt(3)
	v_mfma_f32_32x32x16_bf16 v[48:63], v[154:157], v[104:107], v[48:63]
	ds_read_b128 v[154:157], v129 offset:2048
	s_waitcnt lgkmcnt(3)
	v_mfma_f32_32x32x16_bf16 v[32:47], v[170:173], v[104:107], v[32:47]
	ds_read_b128 v[170:173], v129 offset:6144
	s_waitcnt lgkmcnt(3)
	v_mfma_f32_32x32x16_bf16 v[16:31], v[174:177], v[104:107], v[16:31]
	ds_read_b128 v[174:177], v129 offset:10240
	s_waitcnt lgkmcnt(3)
	v_mfma_f32_32x32x16_bf16 v[0:15], v[178:181], v[104:107], v[0:15]
	ds_read_b128 v[178:181], v129 offset:14336
	s_waitcnt lgkmcnt(3)
	v_mfma_f32_32x32x16_bf16 v[48:63], v[154:157], v[100:103], v[48:63]
	ds_read_b128 v[154:157], v129 offset:3072
	s_waitcnt lgkmcnt(3)
	v_mfma_f32_32x32x16_bf16 v[32:47], v[170:173], v[100:103], v[32:47]
	ds_read_b128 v[170:173], v129 offset:7168
	s_waitcnt lgkmcnt(3)
	v_mfma_f32_32x32x16_bf16 v[16:31], v[174:177], v[100:103], v[16:31]
	ds_read_b128 v[174:177], v129 offset:11264
	s_waitcnt lgkmcnt(3)
	v_mfma_f32_32x32x16_bf16 v[0:15], v[178:181], v[100:103], v[0:15]
	ds_read_b128 v[178:181], v129 offset:15360
	s_waitcnt lgkmcnt(3)
	v_mfma_f32_32x32x16_bf16 v[48:63], v[154:157], v[96:99], v[48:63]
	s_waitcnt lgkmcnt(2)
	v_mfma_f32_32x32x16_bf16 v[32:47], v[170:173], v[96:99], v[32:47]
	s_waitcnt lgkmcnt(1)
	v_mfma_f32_32x32x16_bf16 v[16:31], v[174:177], v[96:99], v[16:31]
	s_waitcnt lgkmcnt(0)
	v_mfma_f32_32x32x16_bf16 v[0:15], v[178:181], v[96:99], v[0:15]
	s_cmp_eq_u32 s24, 8
	s_cbranch_scc0 .LBB0_610
	s_lshl_b32 s8, s20, 2
	s_or_b32 s8, s8, s21
	s_ashr_i32 s9, s8, 31
	s_lshl_b64 s[10:11], s[8:9], 8
	s_add_u32 s9, s10, s17
	s_addc_u32 s8, s11, s18
	s_lshl_b32 s38, s23, 2
	s_waitcnt vmcnt(0)
	v_mov_b32_e32 v67, s8
	v_or_b32_e32 v66, s9, v118
	v_lshl_add_u64 v[64:65], v[120:121], 0, s[38:39]
	v_lshlrev_b64 v[66:67], 11, v[66:67]
	v_lshl_add_u64 v[66:67], v[64:65], 0, v[66:67]
	global_store_dword v[66:67], v48, off
	v_mov_b32_e32 v67, s8
	v_or_b32_e32 v66, s9, v122
	v_lshlrev_b64 v[66:67], 11, v[66:67]
	v_lshl_add_u64 v[66:67], v[64:65], 0, v[66:67]
	global_store_dword v[66:67], v49, off
	v_mov_b32_e32 v49, s8
	v_or_b32_e32 v48, s9, v124
	v_lshlrev_b64 v[48:49], 11, v[48:49]
	v_lshl_add_u64 v[48:49], v[64:65], 0, v[48:49]
	global_store_dword v[48:49], v50, off
	v_mov_b32_e32 v49, s8
	v_or_b32_e32 v48, s9, v126
	v_lshlrev_b64 v[48:49], 11, v[48:49]
	v_lshl_add_u64 v[48:49], v[64:65], 0, v[48:49]
	global_store_dword v[48:49], v51, off
	v_mov_b32_e32 v49, s8
	v_or_b32_e32 v48, s9, v128
	v_lshlrev_b64 v[48:49], 11, v[48:49]
	v_lshl_add_u64 v[48:49], v[64:65], 0, v[48:49]
	global_store_dword v[48:49], v52, off
	v_mov_b32_e32 v49, s8
	v_or_b32_e32 v48, s9, v130
	v_lshlrev_b64 v[48:49], 11, v[48:49]
	v_lshl_add_u64 v[48:49], v[64:65], 0, v[48:49]
	global_store_dword v[48:49], v53, off
	v_mov_b32_e32 v49, s8
	v_or_b32_e32 v48, s9, v132
	v_lshlrev_b64 v[48:49], 11, v[48:49]
	v_lshl_add_u64 v[48:49], v[64:65], 0, v[48:49]
	global_store_dword v[48:49], v54, off
	v_mov_b32_e32 v49, s8
	v_or_b32_e32 v48, s9, v134
	v_lshlrev_b64 v[48:49], 11, v[48:49]
	v_lshl_add_u64 v[48:49], v[64:65], 0, v[48:49]
	global_store_dword v[48:49], v55, off
	v_mov_b32_e32 v49, s8
	v_or_b32_e32 v48, s9, v136
	v_lshlrev_b64 v[48:49], 11, v[48:49]
	v_lshl_add_u64 v[48:49], v[64:65], 0, v[48:49]
	global_store_dword v[48:49], v56, off
	v_mov_b32_e32 v49, s8
	v_or_b32_e32 v48, s9, v138
	v_lshlrev_b64 v[48:49], 11, v[48:49]
	v_lshl_add_u64 v[48:49], v[64:65], 0, v[48:49]
	global_store_dword v[48:49], v57, off
	v_mov_b32_e32 v49, s8
	v_or_b32_e32 v48, s9, v140
	v_lshlrev_b64 v[48:49], 11, v[48:49]
	v_lshl_add_u64 v[48:49], v[64:65], 0, v[48:49]
	global_store_dword v[48:49], v58, off
	v_mov_b32_e32 v49, s8
	v_or_b32_e32 v48, s9, v142
	v_lshlrev_b64 v[48:49], 11, v[48:49]
	v_lshl_add_u64 v[48:49], v[64:65], 0, v[48:49]
	global_store_dword v[48:49], v59, off
	v_mov_b32_e32 v49, s8
	v_or_b32_e32 v48, s9, v144
	v_lshlrev_b64 v[48:49], 11, v[48:49]
	v_lshl_add_u64 v[48:49], v[64:65], 0, v[48:49]
	global_store_dword v[48:49], v60, off
	v_mov_b32_e32 v49, s8
	v_or_b32_e32 v48, s9, v146
	v_lshlrev_b64 v[48:49], 11, v[48:49]
	v_lshl_add_u64 v[48:49], v[64:65], 0, v[48:49]
	global_store_dword v[48:49], v61, off
	v_mov_b32_e32 v49, s8
	v_or_b32_e32 v48, s9, v148
	v_lshlrev_b64 v[48:49], 11, v[48:49]
	v_lshl_add_u64 v[48:49], v[64:65], 0, v[48:49]
	global_store_dword v[48:49], v62, off
	v_mov_b32_e32 v49, s8
	v_or_b32_e32 v48, s9, v150
	v_lshlrev_b64 v[48:49], 11, v[48:49]
	v_lshl_add_u64 v[48:49], v[64:65], 0, v[48:49]
	s_or_b32 s10, s9, 32
	global_store_dword v[48:49], v63, off
	v_mov_b32_e32 v49, s8
	v_or_b32_e32 v48, s10, v118
	v_lshlrev_b64 v[48:49], 11, v[48:49]
	v_lshl_add_u64 v[48:49], v[64:65], 0, v[48:49]
	global_store_dword v[48:49], v32, off
	v_mov_b32_e32 v49, s8
	v_or_b32_e32 v48, s10, v122
	v_lshlrev_b64 v[48:49], 11, v[48:49]
	v_lshl_add_u64 v[48:49], v[64:65], 0, v[48:49]
	global_store_dword v[48:49], v33, off
	v_mov_b32_e32 v33, s8
	v_or_b32_e32 v32, s10, v124
	v_lshlrev_b64 v[32:33], 11, v[32:33]
	v_lshl_add_u64 v[32:33], v[64:65], 0, v[32:33]
	global_store_dword v[32:33], v34, off
	v_mov_b32_e32 v33, s8
	v_or_b32_e32 v32, s10, v126
	v_lshlrev_b64 v[32:33], 11, v[32:33]
	v_lshl_add_u64 v[32:33], v[64:65], 0, v[32:33]
	global_store_dword v[32:33], v35, off
	v_mov_b32_e32 v33, s8
	v_or_b32_e32 v32, s10, v128
	v_lshlrev_b64 v[32:33], 11, v[32:33]
	v_lshl_add_u64 v[32:33], v[64:65], 0, v[32:33]
	global_store_dword v[32:33], v36, off
	v_mov_b32_e32 v33, s8
	v_or_b32_e32 v32, s10, v130
	v_lshlrev_b64 v[32:33], 11, v[32:33]
	v_lshl_add_u64 v[32:33], v[64:65], 0, v[32:33]
	global_store_dword v[32:33], v37, off
	v_mov_b32_e32 v33, s8
	v_or_b32_e32 v32, s10, v132
	v_lshlrev_b64 v[32:33], 11, v[32:33]
	v_lshl_add_u64 v[32:33], v[64:65], 0, v[32:33]
	global_store_dword v[32:33], v38, off
	v_mov_b32_e32 v33, s8
	v_or_b32_e32 v32, s10, v134
	v_lshlrev_b64 v[32:33], 11, v[32:33]
	v_lshl_add_u64 v[32:33], v[64:65], 0, v[32:33]
	global_store_dword v[32:33], v39, off
	v_mov_b32_e32 v33, s8
	v_or_b32_e32 v32, s10, v136
	v_lshlrev_b64 v[32:33], 11, v[32:33]
	v_lshl_add_u64 v[32:33], v[64:65], 0, v[32:33]
	global_store_dword v[32:33], v40, off
	v_mov_b32_e32 v33, s8
	v_or_b32_e32 v32, s10, v138
	v_lshlrev_b64 v[32:33], 11, v[32:33]
	v_lshl_add_u64 v[32:33], v[64:65], 0, v[32:33]
	global_store_dword v[32:33], v41, off
	v_mov_b32_e32 v33, s8
	v_or_b32_e32 v32, s10, v140
	v_lshlrev_b64 v[32:33], 11, v[32:33]
	v_lshl_add_u64 v[32:33], v[64:65], 0, v[32:33]
	global_store_dword v[32:33], v42, off
	v_mov_b32_e32 v33, s8
	v_or_b32_e32 v32, s10, v142
	v_lshlrev_b64 v[32:33], 11, v[32:33]
	v_lshl_add_u64 v[32:33], v[64:65], 0, v[32:33]
	global_store_dword v[32:33], v43, off
	v_mov_b32_e32 v33, s8
	v_or_b32_e32 v32, s10, v144
	v_lshlrev_b64 v[32:33], 11, v[32:33]
	v_lshl_add_u64 v[32:33], v[64:65], 0, v[32:33]
	global_store_dword v[32:33], v44, off
	v_mov_b32_e32 v33, s8
	v_or_b32_e32 v32, s10, v146
	v_lshlrev_b64 v[32:33], 11, v[32:33]
	v_lshl_add_u64 v[32:33], v[64:65], 0, v[32:33]
	global_store_dword v[32:33], v45, off
	v_mov_b32_e32 v33, s8
	v_or_b32_e32 v32, s10, v148
	v_lshlrev_b64 v[32:33], 11, v[32:33]
	v_lshl_add_u64 v[32:33], v[64:65], 0, v[32:33]
	global_store_dword v[32:33], v46, off
	v_mov_b32_e32 v33, s8
	v_or_b32_e32 v32, s10, v150
	v_lshlrev_b64 v[32:33], 11, v[32:33]
	v_lshl_add_u64 v[32:33], v[64:65], 0, v[32:33]
	s_or_b32 s10, s9, 64
	global_store_dword v[32:33], v47, off
	v_mov_b32_e32 v33, s8
	v_or_b32_e32 v32, s10, v118
	v_lshlrev_b64 v[32:33], 11, v[32:33]
	v_lshl_add_u64 v[32:33], v[64:65], 0, v[32:33]
	global_store_dword v[32:33], v16, off
	v_mov_b32_e32 v33, s8
	v_or_b32_e32 v32, s10, v122
	v_lshlrev_b64 v[32:33], 11, v[32:33]
	v_lshl_add_u64 v[32:33], v[64:65], 0, v[32:33]
	global_store_dword v[32:33], v17, off
	v_mov_b32_e32 v17, s8
	v_or_b32_e32 v16, s10, v124
	v_lshlrev_b64 v[16:17], 11, v[16:17]
	v_lshl_add_u64 v[16:17], v[64:65], 0, v[16:17]
	global_store_dword v[16:17], v18, off
	v_mov_b32_e32 v17, s8
	v_or_b32_e32 v16, s10, v126
	v_lshlrev_b64 v[16:17], 11, v[16:17]
	v_lshl_add_u64 v[16:17], v[64:65], 0, v[16:17]
	global_store_dword v[16:17], v19, off
	v_mov_b32_e32 v17, s8
	v_or_b32_e32 v16, s10, v128
	v_lshlrev_b64 v[16:17], 11, v[16:17]
	v_lshl_add_u64 v[16:17], v[64:65], 0, v[16:17]
	global_store_dword v[16:17], v20, off
	v_mov_b32_e32 v17, s8
	v_or_b32_e32 v16, s10, v130
	v_lshlrev_b64 v[16:17], 11, v[16:17]
	v_lshl_add_u64 v[16:17], v[64:65], 0, v[16:17]
	global_store_dword v[16:17], v21, off
	v_mov_b32_e32 v17, s8
	v_or_b32_e32 v16, s10, v132
	v_lshlrev_b64 v[16:17], 11, v[16:17]
	v_lshl_add_u64 v[16:17], v[64:65], 0, v[16:17]
	global_store_dword v[16:17], v22, off
	v_mov_b32_e32 v17, s8
	v_or_b32_e32 v16, s10, v134
	v_lshlrev_b64 v[16:17], 11, v[16:17]
	v_lshl_add_u64 v[16:17], v[64:65], 0, v[16:17]
	global_store_dword v[16:17], v23, off
	v_mov_b32_e32 v17, s8
	v_or_b32_e32 v16, s10, v136
	v_lshlrev_b64 v[16:17], 11, v[16:17]
	v_lshl_add_u64 v[16:17], v[64:65], 0, v[16:17]
	global_store_dword v[16:17], v24, off
	v_mov_b32_e32 v17, s8
	v_or_b32_e32 v16, s10, v138
	v_lshlrev_b64 v[16:17], 11, v[16:17]
	v_lshl_add_u64 v[16:17], v[64:65], 0, v[16:17]
	global_store_dword v[16:17], v25, off
	v_mov_b32_e32 v17, s8
	v_or_b32_e32 v16, s10, v140
	v_lshlrev_b64 v[16:17], 11, v[16:17]
	v_lshl_add_u64 v[16:17], v[64:65], 0, v[16:17]
	global_store_dword v[16:17], v26, off
	v_mov_b32_e32 v17, s8
	v_or_b32_e32 v16, s10, v142
	v_lshlrev_b64 v[16:17], 11, v[16:17]
	v_lshl_add_u64 v[16:17], v[64:65], 0, v[16:17]
	global_store_dword v[16:17], v27, off
	v_mov_b32_e32 v17, s8
	v_or_b32_e32 v16, s10, v144
	v_lshlrev_b64 v[16:17], 11, v[16:17]
	v_lshl_add_u64 v[16:17], v[64:65], 0, v[16:17]
	global_store_dword v[16:17], v28, off
	v_mov_b32_e32 v17, s8
	v_or_b32_e32 v16, s10, v146
	v_lshlrev_b64 v[16:17], 11, v[16:17]
	v_lshl_add_u64 v[16:17], v[64:65], 0, v[16:17]
	global_store_dword v[16:17], v29, off
	v_mov_b32_e32 v17, s8
	v_or_b32_e32 v16, s10, v148
	v_lshlrev_b64 v[16:17], 11, v[16:17]
	v_lshl_add_u64 v[16:17], v[64:65], 0, v[16:17]
	global_store_dword v[16:17], v30, off
	v_mov_b32_e32 v17, s8
	v_or_b32_e32 v16, s10, v150
	v_lshlrev_b64 v[16:17], 11, v[16:17]
	v_lshl_add_u64 v[16:17], v[64:65], 0, v[16:17]
	s_or_b32 s9, s9, 0x60
	global_store_dword v[16:17], v31, off
	v_mov_b32_e32 v17, s8
	v_or_b32_e32 v16, s9, v118
	v_lshlrev_b64 v[16:17], 11, v[16:17]
	v_lshl_add_u64 v[16:17], v[64:65], 0, v[16:17]
	global_store_dword v[16:17], v0, off
	v_mov_b32_e32 v17, s8
	v_or_b32_e32 v16, s9, v122
	v_lshlrev_b64 v[16:17], 11, v[16:17]
	v_lshl_add_u64 v[16:17], v[64:65], 0, v[16:17]
	global_store_dword v[16:17], v1, off
	v_mov_b32_e32 v1, s8
	v_or_b32_e32 v0, s9, v124
	v_lshlrev_b64 v[0:1], 11, v[0:1]
	v_lshl_add_u64 v[0:1], v[64:65], 0, v[0:1]
	global_store_dword v[0:1], v2, off
	v_mov_b32_e32 v1, s8
	v_or_b32_e32 v0, s9, v126
	v_lshlrev_b64 v[0:1], 11, v[0:1]
	v_lshl_add_u64 v[0:1], v[64:65], 0, v[0:1]
	global_store_dword v[0:1], v3, off
	v_mov_b32_e32 v1, s8
	v_or_b32_e32 v0, s9, v128
	v_lshlrev_b64 v[0:1], 11, v[0:1]
	v_lshl_add_u64 v[0:1], v[64:65], 0, v[0:1]
	global_store_dword v[0:1], v4, off
	v_mov_b32_e32 v1, s8
	v_or_b32_e32 v0, s9, v130
	v_lshlrev_b64 v[0:1], 11, v[0:1]
	v_lshl_add_u64 v[0:1], v[64:65], 0, v[0:1]
	global_store_dword v[0:1], v5, off
	v_mov_b32_e32 v1, s8
	v_or_b32_e32 v0, s9, v132
	v_lshlrev_b64 v[0:1], 11, v[0:1]
	v_lshl_add_u64 v[0:1], v[64:65], 0, v[0:1]
	global_store_dword v[0:1], v6, off
	v_mov_b32_e32 v1, s8
	v_or_b32_e32 v0, s9, v134
	v_lshlrev_b64 v[0:1], 11, v[0:1]
	v_lshl_add_u64 v[0:1], v[64:65], 0, v[0:1]
	global_store_dword v[0:1], v7, off
	v_mov_b32_e32 v1, s8
	v_or_b32_e32 v0, s9, v136
	v_lshlrev_b64 v[0:1], 11, v[0:1]
	v_lshl_add_u64 v[0:1], v[64:65], 0, v[0:1]
	global_store_dword v[0:1], v8, off
	v_mov_b32_e32 v1, s8
	v_or_b32_e32 v0, s9, v138
	v_lshlrev_b64 v[0:1], 11, v[0:1]
	v_lshl_add_u64 v[0:1], v[64:65], 0, v[0:1]
	global_store_dword v[0:1], v9, off
	v_mov_b32_e32 v1, s8
	v_or_b32_e32 v0, s9, v140
	v_lshlrev_b64 v[0:1], 11, v[0:1]
	v_lshl_add_u64 v[0:1], v[64:65], 0, v[0:1]
	global_store_dword v[0:1], v10, off
	v_mov_b32_e32 v1, s8
	v_or_b32_e32 v0, s9, v142
	v_lshlrev_b64 v[0:1], 11, v[0:1]
	v_lshl_add_u64 v[0:1], v[64:65], 0, v[0:1]
	global_store_dword v[0:1], v11, off
	v_mov_b32_e32 v1, s8
	v_or_b32_e32 v0, s9, v144
	v_lshlrev_b64 v[0:1], 11, v[0:1]
	v_lshl_add_u64 v[0:1], v[64:65], 0, v[0:1]
	global_store_dword v[0:1], v12, off
	v_mov_b32_e32 v1, s8
	v_or_b32_e32 v0, s9, v146
	v_lshlrev_b64 v[0:1], 11, v[0:1]
	v_lshl_add_u64 v[0:1], v[64:65], 0, v[0:1]
	global_store_dword v[0:1], v13, off
	v_mov_b32_e32 v1, s8
	v_or_b32_e32 v0, s9, v148
	v_lshlrev_b64 v[0:1], 11, v[0:1]
	v_lshl_add_u64 v[0:1], v[64:65], 0, v[0:1]
	global_store_dword v[0:1], v14, off
	v_mov_b32_e32 v1, s8
	v_or_b32_e32 v0, s9, v150
	s_cmp_eq_u32 s22, 0
	v_lshlrev_b64 v[0:1], 11, v[0:1]
	s_cselect_b64 s[8:9], -1, 0
	v_lshl_add_u64 v[0:1], v[64:65], 0, v[0:1]
	s_and_b64 s[10:11], s[0:1], s[8:9]
	global_store_dword v[0:1], v15, off
	s_and_saveexec_b64 s[8:9], s[10:11]
	s_cbranch_execz .LBB0_606
	s_lshl_b32 s10, s21, 8
	s_lshl_b32 s11, s20, 10
	s_or_b32 s10, s10, s11
	v_add_u32_e32 v0, s10, v112
	v_ashrrev_i32_e32 v1, 31, v0
	v_lshl_add_u64 v[0:1], v[0:1], 2, s[6:7]
	global_store_dword v[0:1], v125, off
	s_branch .LBB0_606

.LBB0_747:
	v_cndmask_b32_e64 v64, v80, v64, s[6:7]
	v_cndmask_b32_e64 v65, v81, v65, s[6:7]
	v_cndmask_b32_e64 v66, v82, v66, s[6:7]
	v_cndmask_b32_e64 v67, v83, v67, s[6:7]
	v_cndmask_b32_e64 v68, v84, v68, s[6:7]
	v_cndmask_b32_e64 v69, v85, v69, s[6:7]
	v_cndmask_b32_e64 v70, v86, v70, s[6:7]
	v_cndmask_b32_e64 v71, v87, v71, s[6:7]
	v_cndmask_b32_e64 v72, v88, v72, s[6:7]
	v_cndmask_b32_e64 v73, v89, v73, s[6:7]
	v_cndmask_b32_e64 v74, v90, v74, s[6:7]
	v_cndmask_b32_e64 v75, v91, v75, s[6:7]
	v_cndmask_b32_e64 v76, v92, v76, s[6:7]
	v_cndmask_b32_e64 v77, v93, v77, s[6:7]
	v_cndmask_b32_e64 v78, v94, v78, s[6:7]
	v_cndmask_b32_e64 v79, v95, v79, s[6:7]
	s_waitcnt lgkmcnt(0)
	v_add_f32_e32 v64, v64, v234
	v_add_f32_e32 v65, v65, v235
	v_add_f32_e32 v66, v66, v232
	v_add_f32_e32 v67, v67, v233
	v_add_f32_e32 v68, v68, v230
	v_add_f32_e32 v69, v69, v231
	v_add_f32_e32 v70, v70, v228
	v_add_f32_e32 v71, v71, v229
	v_add_f32_e32 v72, v72, v226
	v_add_f32_e32 v73, v73, v227
	v_add_f32_e32 v74, v74, v224
	v_add_f32_e32 v75, v75, v225
	v_add_f32_e32 v76, v76, v222
	v_add_f32_e32 v77, v77, v223
	v_add_f32_e32 v78, v78, v220
	v_add_f32_e32 v79, v79, v221
	s_mov_b32 s14, 0x2ec00000
	v_add_u32_e32 v92, s21, v210
	s_waitcnt vmcnt(8)
	v_mfma_f32_32x32x16_bf16 v[64:79], v[144:147], v[140:143], v[64:79]
	v_mfma_f32_32x32x16_bf16 v[64:79], v[148:151], v[136:139], v[64:79]
	v_mfma_f32_32x32x16_bf16 v[64:79], v[152:155], v[132:135], v[64:79]
	v_mfma_f32_32x32x16_bf16 v[64:79], v[156:159], v[128:131], v[64:79]
	s_nop 11
	v_cvt_pk_bf16_f32 v80, v64, v65
	v_cvt_pk_bf16_f32 v81, v66, v67
	v_cvt_pk_bf16_f32 v82, v68, v69
	v_cvt_pk_bf16_f32 v83, v70, v71
	v_cvt_pk_bf16_f32 v84, v72, v73
	v_cvt_pk_bf16_f32 v85, v74, v75
	v_cvt_pk_bf16_f32 v86, v76, v77
	v_cvt_pk_bf16_f32 v87, v78, v79
	ds_write_b16 v244, v80
	ds_write_b16_d16_hi v244, v80 offset:80
	ds_write_b16 v244, v81 offset:160
	ds_write_b16_d16_hi v244, v81 offset:240
	ds_write_b16 v244, v82 offset:640
	ds_write_b16_d16_hi v244, v82 offset:720
	ds_write_b16 v244, v83 offset:800
	ds_write_b16_d16_hi v244, v83 offset:880
	ds_write_b16 v244, v84 offset:1280
	ds_write_b16_d16_hi v244, v84 offset:1360
	ds_write_b16 v244, v85 offset:1440
	ds_write_b16_d16_hi v244, v85 offset:1520
	ds_write_b16 v244, v86 offset:1920
	ds_write_b16_d16_hi v244, v86 offset:2000
	ds_write_b16 v244, v87 offset:2080
	ds_write_b16_d16_hi v244, v87 offset:2160
	v_lshl_add_u64 v[88:89], v[242:243], 0, s[12:13]
	s_mov_b32 s14, 0x2ec00000
	v_add_co_u32_e32 v88, vcc, s14, v88
	s_nop 1
	v_addc_co_u32_e32 v89, vcc, 0, v89, vcc
	ds_read_b128 v[64:67], v245
	ds_read_b128 v[68:71], v245 offset:1280
	v_add_co_u32_e32 v90, vcc, 0x10000, v88
	s_nop 1
	v_addc_co_u32_e32 v91, vcc, 0, v89, vcc
	s_waitcnt lgkmcnt(0)
	global_store_dwordx4 v[88:89], v[64:67], off
	global_store_dwordx4 v[90:91], v[68:71], off
	s_and_b64 vcc, exec, s[4:5]
	ds_read_b128 v[64:67], v92
	ds_read_b128 v[68:71], v92 offset:32
	ds_read_b128 v[72:75], v92 offset:64
	ds_read_b128 v[76:79], v92 offset:96
	ds_read_b128 v[80:83], v92 offset:128
	ds_read_b128 v[84:87], v92 offset:160
	ds_read_b128 v[88:91], v92 offset:192
	ds_read_b128 v[220:223], v92 offset:224
	s_waitcnt lgkmcnt(4)
	v_pk_mul_f32 v[0:1], v[0:1], v[64:65]
	v_pk_mul_f32 v[2:3], v[2:3], v[66:67]
	v_pk_mul_f32 v[4:5], v[4:5], v[68:69]
	v_pk_mul_f32 v[6:7], v[6:7], v[70:71]
	v_pk_mul_f32 v[8:9], v[8:9], v[72:73]
	v_pk_mul_f32 v[10:11], v[10:11], v[74:75]
	v_pk_mul_f32 v[12:13], v[12:13], v[76:77]
	v_pk_mul_f32 v[14:15], v[14:15], v[78:79]
	ds_read_b128 v[64:67], v92 offset:256
	ds_read_b128 v[68:71], v92 offset:288
	ds_read_b128 v[72:75], v92 offset:320
	ds_read_b128 v[76:79], v92 offset:352
	s_waitcnt lgkmcnt(4)
	v_pk_mul_f32 v[16:17], v[16:17], v[80:81]
	v_pk_mul_f32 v[18:19], v[18:19], v[82:83]
	v_pk_mul_f32 v[20:21], v[20:21], v[84:85]
	v_pk_mul_f32 v[22:23], v[22:23], v[86:87]
	v_pk_mul_f32 v[24:25], v[24:25], v[88:89]
	v_pk_mul_f32 v[26:27], v[26:27], v[90:91]
	v_pk_mul_f32 v[28:29], v[28:29], v[220:221]
	v_pk_mul_f32 v[30:31], v[30:31], v[222:223]
	ds_read_b128 v[80:83], v92 offset:384
	ds_read_b128 v[84:87], v92 offset:416
	ds_read_b128 v[88:91], v92 offset:448
	ds_read_b128 v[220:223], v92 offset:480
	s_waitcnt lgkmcnt(4)
	v_pk_mul_f32 v[32:33], v[32:33], v[64:65]
	v_pk_mul_f32 v[34:35], v[34:35], v[66:67]
	v_pk_mul_f32 v[36:37], v[36:37], v[68:69]
	v_pk_mul_f32 v[38:39], v[38:39], v[70:71]
	v_pk_mul_f32 v[40:41], v[40:41], v[72:73]
	v_pk_mul_f32 v[42:43], v[42:43], v[74:75]
	v_pk_mul_f32 v[44:45], v[44:45], v[76:77]
	v_pk_mul_f32 v[46:47], v[46:47], v[78:79]
	ds_read_b128 v[64:67], v199
	ds_read_b128 v[68:71], v199 offset:4096
	ds_read_b128 v[72:75], v199 offset:8192
	ds_read_b128 v[76:79], v199 offset:12288
	s_waitcnt lgkmcnt(4)
	v_pk_mul_f32 v[48:49], v[48:49], v[80:81]
	v_pk_mul_f32 v[50:51], v[50:51], v[82:83]
	v_pk_mul_f32 v[52:53], v[52:53], v[84:85]
	v_pk_mul_f32 v[54:55], v[54:55], v[86:87]
	v_pk_mul_f32 v[56:57], v[56:57], v[88:89]
	v_pk_mul_f32 v[58:59], v[58:59], v[90:91]
	v_pk_mul_f32 v[60:61], v[60:61], v[220:221]
	v_pk_mul_f32 v[62:63], v[62:63], v[222:223]
	s_waitcnt lgkmcnt(3)
	v_mfma_f32_32x32x16_bf16 v[0:15], v[64:67], v[140:143], v[0:15]
	ds_read_b128 v[64:67], v199 offset:1024
	s_waitcnt lgkmcnt(3)
	v_mfma_f32_32x32x16_bf16 v[16:31], v[68:71], v[140:143], v[16:31]
	ds_read_b128 v[68:71], v199 offset:5120
	s_waitcnt lgkmcnt(3)
	v_mfma_f32_32x32x16_bf16 v[32:47], v[72:75], v[140:143], v[32:47]
	ds_read_b128 v[72:75], v199 offset:9216
	s_waitcnt lgkmcnt(3)
	v_mfma_f32_32x32x16_bf16 v[48:63], v[76:79], v[140:143], v[48:63]
	ds_read_b128 v[76:79], v199 offset:13312
	s_waitcnt lgkmcnt(3)
	v_mfma_f32_32x32x16_bf16 v[0:15], v[64:67], v[136:139], v[0:15]
	ds_read_b128 v[64:67], v199 offset:2048
	s_waitcnt lgkmcnt(3)
	v_mfma_f32_32x32x16_bf16 v[16:31], v[68:71], v[136:139], v[16:31]
	ds_read_b128 v[68:71], v199 offset:6144
	s_waitcnt lgkmcnt(3)
	v_mfma_f32_32x32x16_bf16 v[32:47], v[72:75], v[136:139], v[32:47]
	ds_read_b128 v[72:75], v199 offset:10240
	s_waitcnt lgkmcnt(3)
	v_mfma_f32_32x32x16_bf16 v[48:63], v[76:79], v[136:139], v[48:63]
	ds_read_b128 v[76:79], v199 offset:14336
	s_waitcnt lgkmcnt(3)
	v_mfma_f32_32x32x16_bf16 v[0:15], v[64:67], v[132:135], v[0:15]
	ds_read_b128 v[64:67], v199 offset:3072
	s_waitcnt lgkmcnt(3)
	v_mfma_f32_32x32x16_bf16 v[16:31], v[68:71], v[132:135], v[16:31]
	ds_read_b128 v[68:71], v199 offset:7168
	s_waitcnt lgkmcnt(3)
	v_mfma_f32_32x32x16_bf16 v[32:47], v[72:75], v[132:135], v[32:47]
	ds_read_b128 v[72:75], v199 offset:11264
	s_waitcnt lgkmcnt(3)
	v_mfma_f32_32x32x16_bf16 v[48:63], v[76:79], v[132:135], v[48:63]
	ds_read_b128 v[76:79], v199 offset:15360
	s_waitcnt lgkmcnt(3)
	v_mfma_f32_32x32x16_bf16 v[0:15], v[64:67], v[128:131], v[0:15]
	s_waitcnt lgkmcnt(2)
	v_mfma_f32_32x32x16_bf16 v[16:31], v[68:71], v[128:131], v[16:31]
	s_waitcnt lgkmcnt(1)
	v_mfma_f32_32x32x16_bf16 v[32:47], v[72:75], v[128:131], v[32:47]
	s_waitcnt lgkmcnt(0)
	v_mfma_f32_32x32x16_bf16 v[48:63], v[76:79], v[128:131], v[48:63]
	s_cbranch_vccnz .LBB0_738
	s_xor_b32 s4, s11, 0x8000
	v_add_u32_e32 v64, s4, v177
	s_waitcnt vmcnt(6)
	ds_write_b128 v64, v[96:99]
	ds_write_b128 v64, v[104:107] offset:8192
	ds_write_b128 v64, v[112:115] offset:16384
	ds_write_b128 v64, v[120:123] offset:24576
	s_branch .LBB0_738
